# attention K/V prefetch: counted vmcnt waits (Q waited once before the loop; each LDS write pass waits only for its own register set)
# baseline (speedup 1.0000x reference)
.Lattn_nosw_2:
	ds_write_b128 v188, v[20:23] offset:14336
	v_or_b32_e32 v210, v204, v79
	v_mov_b32_e32 v2, v3
	v_mov_b32_e32 v4, v3
	v_mov_b32_e32 v5, v3
	v_add_u32_e32 v212, v8, v76
	v_add_u32_e32 v213, v24, v9
	v_mov_b64_e32 v[22:23], v[6:7]
	v_mov_b64_e32 v[10:11], v[6:7]
	v_mov_b64_e32 v[26:27], v[6:7]
	v_mov_b64_e32 v[14:15], v[6:7]
	v_mov_b64_e32 v[30:31], v[6:7]
	v_mov_b64_e32 v[18:19], v[6:7]
	v_mov_b64_e32 v[98:99], v[6:7]
	s_mov_b32 s61, 3
	v_ashrrev_i32_e32 v167, 31, v166
	v_ashrrev_i32_e32 v1, 31, v0
	v_add_u32_e32 v209, 2, v205
	v_or_b32_e32 v189, 31, v204
	v_lshlrev_b32_e32 v187, 2, v83
	v_or_b32_e32 v211, 16, v210
	v_mov_b32_e32 v215, 0xf149f2ca
	s_movk_i32 s56, 0xc0
	s_mov_b64 s[54:55], 0
	v_mov_b64_e32 v[20:21], v[4:5]
	v_mov_b64_e32 v[8:9], v[4:5]
	v_mov_b64_e32 v[24:25], v[4:5]
	v_mov_b64_e32 v[12:13], v[4:5]
	v_mov_b64_e32 v[28:29], v[4:5]
	v_mov_b64_e32 v[16:17], v[4:5]
	v_mov_b64_e32 v[96:97], v[4:5]
	v_mov_b32_e32 v214, 0xf149f2ca
	v_mov_b64_e32 v[164:165], v[2:3]
	s_waitcnt lgkmcnt(0)
	s_barrier
	s_mov_b32 s101, 0xff800000
	v_mov_b32_e32 v240, 0
	v_mov_b32_e32 v241, 0
	v_mov_b32_e32 v242, 0
	v_mov_b32_e32 v243, 0
	v_mov_b32_e32 v244, 0
	v_mov_b32_e32 v245, 0
	v_mov_b32_e32 v246, 0
	v_mov_b32_e32 v247, 0
	s_waitcnt vmcnt(5)
	s_branch .LBB0_856

.LBB0_858:
	s_or_b64 exec, exec, s[0:1]
	s_add_i32 s0, s56, 0xffffff40
	v_cmp_le_i32_e64 s[0:1], s0, v189
	s_and_saveexec_b64 s[40:41], s[0:1]
	s_cbranch_execz .LBB0_862
	ds_read_b128 v[100:103], v212
	ds_read_b128 v[104:107], v212 offset:64
	ds_read_b128 v[108:111], v212 offset:128
	ds_read_b128 v[112:115], v212 offset:3584
	ds_read_b128 v[116:119], v212 offset:3648
	ds_read_b128 v[120:123], v212 offset:3712
	ds_read_b128 v[124:127], v212 offset:7168
	ds_read_b128 v[128:131], v212 offset:7232
	ds_read_b128 v[132:135], v212 offset:7296
	ds_read_b128 v[216:219], v212 offset:10752
	ds_read_b128 v[220:223], v212 offset:10816
	ds_read_b128 v[224:227], v212 offset:10880
	s_waitcnt lgkmcnt(11)
	v_mfma_f32_16x16x32_bf16 v[136:139], v[100:103], v[32:35], v[240:243]
	s_nop 0
	v_mfma_f32_16x16x32_bf16 v[100:103], v[100:103], v[44:47], v[244:247]
	s_waitcnt lgkmcnt(10)
	v_mfma_f32_16x16x32_bf16 v[100:103], v[104:107], v[48:51], v[100:103]
	s_waitcnt lgkmcnt(9)
	v_mfma_f32_16x16x32_bf16 v[144:147], v[108:111], v[52:55], v[100:103]
	s_waitcnt lgkmcnt(8)
	v_mfma_f32_16x16x32_bf16 v[100:103], v[112:115], v[32:35], v[240:243]
	s_waitcnt lgkmcnt(7)
	v_mfma_f32_16x16x32_bf16 v[100:103], v[116:119], v[36:39], v[100:103]
	s_waitcnt lgkmcnt(6)
	v_mfma_f32_16x16x32_bf16 v[156:159], v[120:123], v[40:43], v[100:103]
	v_mfma_f32_16x16x32_bf16 v[100:103], v[112:115], v[44:47], v[244:247]
	v_mfma_f32_16x16x32_bf16 v[100:103], v[116:119], v[48:51], v[100:103]
	v_mfma_f32_16x16x32_bf16 v[140:143], v[120:123], v[52:55], v[100:103]
	s_waitcnt lgkmcnt(5)
	v_mfma_f32_16x16x32_bf16 v[100:103], v[124:127], v[32:35], v[240:243]
	s_waitcnt lgkmcnt(4)
	v_mfma_f32_16x16x32_bf16 v[100:103], v[128:131], v[36:39], v[100:103]
	s_waitcnt lgkmcnt(3)
	v_mfma_f32_16x16x32_bf16 v[152:155], v[132:135], v[40:43], v[100:103]
	v_mfma_f32_16x16x32_bf16 v[100:103], v[124:127], v[44:47], v[244:247]
	v_mfma_f32_16x16x32_bf16 v[136:139], v[104:107], v[36:39], v[136:139]
	v_mfma_f32_16x16x32_bf16 v[100:103], v[128:131], v[48:51], v[100:103]
	v_mfma_f32_16x16x32_bf16 v[160:163], v[108:111], v[40:43], v[136:139]
	v_mfma_f32_16x16x32_bf16 v[136:139], v[132:135], v[52:55], v[100:103]
	s_waitcnt lgkmcnt(2)
	v_mfma_f32_16x16x32_bf16 v[100:103], v[216:219], v[32:35], v[240:243]
	s_waitcnt lgkmcnt(1)
	v_mfma_f32_16x16x32_bf16 v[100:103], v[220:223], v[36:39], v[100:103]
	s_waitcnt lgkmcnt(0)
	v_mfma_f32_16x16x32_bf16 v[148:151], v[224:227], v[40:43], v[100:103]
	v_mfma_f32_16x16x32_bf16 v[100:103], v[216:219], v[44:47], v[244:247]
	v_mfma_f32_16x16x32_bf16 v[100:103], v[220:223], v[48:51], v[100:103]
	v_mfma_f32_16x16x32_bf16 v[132:135], v[224:227], v[52:55], v[100:103]
	v_add_u32_e32 v2, 0x3800, v213
	s_nop 5
	ds_read2_b64 v[100:103], v2 offset1:4
	ds_read2_b64 v[104:107], v2 offset0:8 offset1:12
	v_add_u32_e32 v2, 0x4000, v213
	ds_read2_b64 v[108:111], v2 offset0:32 offset1:36
	ds_read2_b64 v[112:115], v2 offset0:40 offset1:44
	v_add_u32_e32 v2, 0x4800, v213
	ds_read2_b64 v[120:123], v2 offset0:64 offset1:68
	ds_read2_b64 v[124:127], v2 offset0:72 offset1:76
	v_add_u32_e32 v2, 0x5000, v213
	ds_read2_b64 v[128:131], v2 offset0:96 offset1:100
	ds_read2_b64 v[116:119], v2 offset0:104 offset1:108
	s_add_i32 s0, s56, 0xffffff7f
	v_cmp_gt_i32_e64 s[0:1], s0, v204
	s_and_saveexec_b64 s[58:59], s[0:1]
	s_cbranch_execz .LBB0_861
	v_add_u32_e32 v216, s56, v187
	v_add_u32_e32 v217, 0xffffff40, v216
	v_mov_b32_e32 v2, s29
	v_cmp_gt_i32_e64 s[0:1], v217, v210
	v_cmp_lt_i32_e64 s[42:43], v217, v210
	v_add_u32_e32 v218, 0xffffff42, v216
	v_cndmask_b32_e64 v2, v160, v2, s[0:1]
	v_cndmask_b32_e64 v160, v2, v160, s[42:43]
	v_cndmask_b32_e64 v161, v203, v161, s[42:43]
	v_cmp_le_i32_e64 s[42:43], v218, v210
	v_add_u32_e32 v219, 0xffffff43, v216
	v_mov_b32_e32 v2, s29
	v_cndmask_b32_e64 v162, v203, v162, s[42:43]
	v_cmp_le_i32_e64 s[42:43], v219, v210
	v_add_u32_e32 v220, 0xffffff63, v216
	s_nop 0
	v_cndmask_b32_e64 v163, v203, v163, s[42:43]
	v_cmp_gt_i32_e64 s[42:43], v217, v211
	s_nop 1
	v_cndmask_b32_e64 v2, v144, v2, s[42:43]
	v_cmp_lt_i32_e64 s[42:43], v217, v211
	v_add_u32_e32 v217, 0xffffff50, v216
	s_nop 0
	v_cndmask_b32_e64 v144, v2, v144, s[42:43]
	v_cndmask_b32_e64 v145, v203, v145, s[42:43]
	v_cmp_le_i32_e64 s[42:43], v218, v211
	v_mov_b32_e32 v2, s29
	v_add_u32_e32 v218, 0xffffff52, v216
	v_cndmask_b32_e64 v146, v203, v146, s[42:43]
	v_cmp_le_i32_e64 s[42:43], v219, v211
	v_cndmask_b32_e64 v140, v140, v2, s[0:1]
	v_add_u32_e32 v219, 0xffffff53, v216
	v_cndmask_b32_e64 v147, v203, v147, s[42:43]
	v_cmp_gt_i32_e64 s[42:43], v217, v210
	v_add_u32_e32 v217, 0xffffff51, v216
	v_cmp_le_i32_e64 s[0:1], v217, v211
	v_cndmask_b32_e64 v156, v156, v2, s[42:43]
	v_cmp_le_i32_e64 s[42:43], v217, v210
	v_cndmask_b32_e64 v141, v203, v141, s[0:1]
	v_cmp_le_i32_e64 s[0:1], v218, v211
	v_add_u32_e32 v217, 0xffffff60, v216
	v_cndmask_b32_e64 v157, v203, v157, s[42:43]
	v_cndmask_b32_e64 v142, v203, v142, s[0:1]
	v_cmp_le_i32_e64 s[0:1], v219, v211
	v_cmp_le_i32_e64 s[42:43], v218, v210
	v_add_u32_e32 v218, 0xffffff61, v216
	v_cndmask_b32_e64 v143, v203, v143, s[0:1]
	v_cmp_gt_i32_e64 s[0:1], v217, v210
	v_cndmask_b32_e64 v158, v203, v158, s[42:43]
	v_cmp_le_i32_e64 s[42:43], v219, v210
	v_cndmask_b32_e64 v152, v152, v2, s[0:1]
	v_cmp_le_i32_e64 s[0:1], v218, v210
	v_add_u32_e32 v219, 0xffffff62, v216
	v_cndmask_b32_e64 v159, v203, v159, s[42:43]
	v_cndmask_b32_e64 v153, v203, v153, s[0:1]
	v_cmp_le_i32_e64 s[0:1], v219, v210
	s_nop 1
	v_cndmask_b32_e64 v154, v203, v154, s[0:1]
	v_cmp_le_i32_e64 s[0:1], v220, v210
	s_nop 1
	v_cndmask_b32_e64 v155, v203, v155, s[0:1]
	v_cmp_gt_i32_e64 s[0:1], v217, v211
	v_add_u32_e32 v217, 0xffffff70, v216
	s_nop 0
	v_cndmask_b32_e64 v136, v136, v2, s[0:1]
	v_cmp_le_i32_e64 s[0:1], v218, v211
	v_add_u32_e32 v218, 0xffffff71, v216
	s_nop 0
	v_cndmask_b32_e64 v137, v203, v137, s[0:1]
	v_cmp_le_i32_e64 s[0:1], v219, v211
	v_add_u32_e32 v219, 0xffffff72, v216
	v_add_u32_e32 v216, 0xffffff73, v216
	v_cndmask_b32_e64 v138, v203, v138, s[0:1]
	v_cmp_le_i32_e64 s[0:1], v220, v211
	s_nop 1
	v_cndmask_b32_e64 v139, v203, v139, s[0:1]
	v_cmp_gt_i32_e64 s[0:1], v217, v210
	s_nop 1
	v_cndmask_b32_e64 v148, v148, v2, s[0:1]
	v_cmp_le_i32_e64 s[0:1], v218, v210
	s_nop 1
	v_cndmask_b32_e64 v149, v203, v149, s[0:1]
	v_cmp_le_i32_e64 s[0:1], v219, v210
	s_nop 1
	v_cndmask_b32_e64 v150, v203, v150, s[0:1]
	v_cmp_le_i32_e64 s[0:1], v216, v210
	s_nop 1
	v_cndmask_b32_e64 v151, v203, v151, s[0:1]
	v_cmp_gt_i32_e64 s[0:1], v217, v211
	s_nop 1
	v_cndmask_b32_e64 v132, v132, v2, s[0:1]
	v_cmp_le_i32_e64 s[0:1], v218, v211
	s_nop 1
	v_cndmask_b32_e64 v133, v203, v133, s[0:1]
	v_cmp_le_i32_e64 s[0:1], v219, v211
	s_nop 1
	v_cndmask_b32_e64 v134, v203, v134, s[0:1]
	v_cmp_le_i32_e64 s[0:1], v216, v211
	s_nop 1
	v_cndmask_b32_e64 v135, v203, v135, s[0:1]

.LBB0_862:
	s_or_b64 exec, exec, s[40:41]
	v_cmp_lt_u32_e64 s[0:1], s61, v209
	s_cbranch_vccz .Law_m0
	s_waitcnt vmcnt(5)
	s_branch .Law_m1

.Law_m1:
	ds_write_b128 v206, v[60:63] offset:23552
	ds_write_b128 v207, v[56:59] offset:23552
	ds_write_b128 v208, v[64:67] offset:23552
	s_bitcmp1_b32 s100, 0
	s_cbranch_scc0 .Lattn_nosw_3
	v_swap_b32 v68, v70
	v_swap_b32 v69, v71
.Lattn_nosw_3:
	ds_write_b128 v186, v[68:71] offset:37888
	s_nop 0
	s_bitcmp1_b32 s100, 0
	s_cbranch_scc0 .Lattn_nosw_4
	v_swap_b32 v72, v74
	v_swap_b32 v73, v75
.Lattn_nosw_4:
	ds_write_b128 v188, v[72:75] offset:37888
	s_waitcnt lgkmcnt(0)
	s_barrier
	s_bitset0_b32 s100, 4
	s_and_saveexec_b64 s[12:13], s[0:1]
	s_cbranch_execz .LBB0_864
	s_bitset1_b32 s100, 4
	s_mov_b32 s57, s35
	v_mad_u64_u32 v[64:65], s[0:1], s56, v202, v[174:175]
	v_lshl_add_u64 v[72:73], s[56:57], 1, v[184:185]
	v_lshl_add_u64 v[56:57], v[168:169], 1, v[64:65]
	v_lshl_add_u64 v[58:59], v[170:171], 1, v[64:65]
	v_lshl_add_u64 v[64:65], v[172:173], 1, v[64:65]
	v_lshl_add_u64 v[68:69], v[176:177], 1, v[72:73]
	v_lshl_add_u64 v[72:73], v[182:183], 1, v[72:73]
	global_load_dwordx4 v[60:63], v[56:57], off
	s_nop 0
	global_load_dwordx4 v[56:59], v[58:59], off
	s_nop 0
	global_load_dwordx4 v[64:67], v[64:65], off
	s_nop 0
	global_load_dwordx4 v[68:71], v[68:69], off
	s_nop 0
	global_load_dwordx4 v[72:75], v[72:73], off

.LBB0_868:
	s_or_b64 exec, exec, s[40:41]
	s_and_saveexec_b64 s[0:1], vcc
	s_cbranch_execz .LBB0_855
	s_bitcmp1_b32 s100, 4
	s_cbranch_scc0 .Law_e0
	s_waitcnt vmcnt(5)
	s_branch .Law_e1

.Law_e1:
	ds_write_b128 v206, v[80:83]
	ds_write_b128 v207, v[76:79]
	ds_write_b128 v208, v[84:87]
	s_bitcmp1_b32 s100, 0
	s_cbranch_scc0 .Lattn_nosw_5
	v_swap_b32 v88, v90
	v_swap_b32 v89, v91
